# v107 + hand-written W_out/W_fc1/W_fc2 transposes (n-major tile mapping, all nine tiles prefetched at the path head)
# baseline (speedup 1.0000x reference)
.Ltp_fast:
	s_sub_u32 s24, s74, 0xb0
	s_subb_u32 s25, s75, 0
	s_load_dwordx4 s[56:59], s[24:25], 0x70
	s_load_dwordx4 s[92:95], s[24:25], 0x80
	s_waitcnt lgkmcnt(0)
	v_lshrrev_b32_e32 v40, 4, v179
	v_and_b32_e32 v41, 15, v179
	v_lshlrev_b32_e32 v41, 4, v41
	v_lshl_add_u32 v42, v40, 12, v41
	v_lshl_add_u32 v43, v40, 14, v41
	v_and_b32_e32 v40, 7, v179
	v_lshlrev_b32_e32 v40, 5, v40
	s_and_b32 s0, s96, 15
	s_lshr_b32 s1, s96, 4
	s_and_b32 s2, s96, 63
	s_lshr_b32 s3, s96, 6
	s_lshl_b32 s6, s0, 18
	s_lshl_b32 s9, s1, 8
	s_add_u32 s6, s6, s9
	s_add_u32 s48, s56, s6
	s_addc_u32 s49, s57, 0
	s_add_u32 s44, s48, 0x20000
	s_addc_u32 s45, s49, 0
	global_load_dwordx4 v[44:47], v42, s[48:49]
	global_load_dwordx4 v[48:51], v42, s[44:45]
	s_add_u32 s6, s3, 0
	s_lshl_b32 s6, s6, 20
	s_lshl_b32 s9, s2, 8
	s_add_u32 s6, s6, s9
	s_add_u32 s48, s92, s6
	s_addc_u32 s49, s93, 0
	s_add_u32 s44, s48, 0x80000
	s_addc_u32 s45, s49, 0
	global_load_dwordx4 v[52:55], v43, s[48:49]
	global_load_dwordx4 v[56:59], v43, s[44:45]
	s_add_u32 s6, s3, 4
	s_lshl_b32 s6, s6, 20
	s_lshl_b32 s9, s2, 8
	s_add_u32 s6, s6, s9
	s_add_u32 s48, s92, s6
	s_addc_u32 s49, s93, 0
	s_add_u32 s44, s48, 0x80000
	s_addc_u32 s45, s49, 0
	global_load_dwordx4 v[60:63], v43, s[48:49]
	global_load_dwordx4 v[64:67], v43, s[44:45]
	s_add_u32 s6, s3, 8
	s_lshl_b32 s6, s6, 20
	s_lshl_b32 s9, s2, 8
	s_add_u32 s6, s6, s9
	s_add_u32 s48, s92, s6
	s_addc_u32 s49, s93, 0
	s_add_u32 s44, s48, 0x80000
	s_addc_u32 s45, s49, 0
	global_load_dwordx4 v[68:71], v43, s[48:49]
	global_load_dwordx4 v[72:75], v43, s[44:45]
	s_add_u32 s6, s3, 12
	s_lshl_b32 s6, s6, 20
	s_lshl_b32 s9, s2, 8
	s_add_u32 s6, s6, s9
	s_add_u32 s48, s92, s6
	s_addc_u32 s49, s93, 0
	s_add_u32 s44, s48, 0x80000
	s_addc_u32 s45, s49, 0
	global_load_dwordx4 v[76:79], v43, s[48:49]
	global_load_dwordx4 v[80:83], v43, s[44:45]
	s_add_u32 s6, s1, 0
	s_lshl_b32 s6, s6, 18
	s_lshl_b32 s9, s0, 8
	s_add_u32 s6, s6, s9
	s_add_u32 s48, s94, s6
	s_addc_u32 s49, s95, 0
	s_add_u32 s44, s48, 0x20000
	s_addc_u32 s45, s49, 0
	global_load_dwordx4 v[84:87], v42, s[48:49]
	global_load_dwordx4 v[88:91], v42, s[44:45]
	s_add_u32 s6, s1, 16
	s_lshl_b32 s6, s6, 18
	s_lshl_b32 s9, s0, 8
	s_add_u32 s6, s6, s9
	s_add_u32 s48, s94, s6
	s_addc_u32 s49, s95, 0
	s_add_u32 s44, s48, 0x20000
	s_addc_u32 s45, s49, 0
	global_load_dwordx4 v[92:95], v42, s[48:49]
	global_load_dwordx4 v[96:99], v42, s[44:45]
	s_add_u32 s6, s1, 32
	s_lshl_b32 s6, s6, 18
	s_lshl_b32 s9, s0, 8
	s_add_u32 s6, s6, s9
	s_add_u32 s48, s94, s6
	s_addc_u32 s49, s95, 0
	s_add_u32 s44, s48, 0x20000
	s_addc_u32 s45, s49, 0
	global_load_dwordx4 v[100:103], v42, s[48:49]
	global_load_dwordx4 v[104:107], v42, s[44:45]
	s_add_u32 s6, s1, 48
	s_lshl_b32 s6, s6, 18
	s_lshl_b32 s9, s0, 8
	s_add_u32 s6, s6, s9
	s_add_u32 s48, s94, s6
	s_addc_u32 s49, s95, 0
	s_add_u32 s44, s48, 0x20000
	s_addc_u32 s45, s49, 0
	global_load_dwordx4 v[108:111], v42, s[48:49]
	global_load_dwordx4 v[112:115], v42, s[44:45]
	s_add_u32 s6, s3, 0
	s_lshl_b32 s6, s6, 8
	s_add_u32 s48, s58, s6
	s_addc_u32 s49, s59, 0
	global_load_dwordx4 v[116:119], v40, s[48:49]
	global_load_dwordx4 v[120:123], v40, s[48:49] offset:16
	s_add_u32 s6, s3, 4
	s_lshl_b32 s6, s6, 8
	s_add_u32 s48, s58, s6
	s_addc_u32 s49, s59, 0
	global_load_dwordx4 v[124:127], v40, s[48:49]
	global_load_dwordx4 v[128:131], v40, s[48:49] offset:16
	s_add_u32 s6, s3, 8
	s_lshl_b32 s6, s6, 8
	s_add_u32 s48, s58, s6
	s_addc_u32 s49, s59, 0
	global_load_dwordx4 v[132:135], v40, s[48:49]
	global_load_dwordx4 v[136:139], v40, s[48:49] offset:16
	s_add_u32 s6, s3, 12
	s_lshl_b32 s6, s6, 8
	s_add_u32 s48, s58, s6
	s_addc_u32 s49, s59, 0
	global_load_dwordx4 v[140:143], v40, s[48:49]
	global_load_dwordx4 v[144:147], v40, s[48:49] offset:16
	s_sub_u32 s24, s74, 0xb0
	s_subb_u32 s25, s75, 0
	s_load_dwordx2 s[28:29], s[24:25], 0xa0
	v_lshrrev_b32_e32 v0, 4, v179
	v_and_b32_e32 v1, 15, v179
	v_lshrrev_b32_e32 v2, 3, v179
	v_and_b32_e32 v3, 7, v179
	s_movk_i32 s20, 0x104
	v_mul_u32_u24_e32 v4, s20, v0
	v_lshl_add_u32 v4, v1, 4, v4
	s_movk_i32 s20, 0x820
	v_mul_u32_u24_e32 v5, s20, v3
	v_lshl_add_u32 v5, v2, 2, v5
	v_add_u32_e32 v8, 0x4400, v4
	v_add_u32_e32 v9, 0x6480, v4
	v_add_u32_e32 v12, 0x4400, v5
	v_add_u32_e32 v13, 0x4810, v5
	v_add_u32_e32 v10, 0x0, v4
	v_add_u32_e32 v11, 0x2080, v4
	v_add_u32_e32 v14, 0x0, v5
	v_add_u32_e32 v15, 0x410, v5
	v_lshlrev_b32_e32 v6, 4, v3
	v_lshl_add_u32 v7, v2, 13, v6
	v_lshl_add_u32 v6, v2, 11, v6
	s_and_b32 s0, s96, 15
	s_lshr_b32 s1, s96, 4
	s_and_b32 s2, s96, 63
	s_lshr_b32 s3, s96, 6
	s_waitcnt vmcnt(0) lgkmcnt(0)
	s_lshl_b32 s6, s1, 17
	s_lshl_b32 s9, s0, 7
	s_add_u32 s6, s6, s9
	s_add_u32 s6, s6, 0x1c400000
	s_add_u32 s48, s28, s6
	s_addc_u32 s49, s29, 0
	ds_write2_b32 v8, v44, v45 offset1:1
	ds_write2_b32 v8, v46, v47 offset0:2 offset1:3
	ds_write2_b32 v9, v48, v49 offset1:1
	ds_write2_b32 v9, v50, v51 offset0:2 offset1:3
	s_waitcnt lgkmcnt(0)
	s_barrier
	ds_read2_b32 v[16:17], v12 offset1:65
	ds_read2_b32 v[18:19], v12 offset0:130 offset1:195
	ds_read2_b32 v[20:21], v13 offset1:65
	ds_read2_b32 v[22:23], v13 offset0:130 offset1:195
	s_waitcnt lgkmcnt(0)
	v_cvt_pk_bf16_f32 v24, v16, v17
	v_cvt_pk_bf16_f32 v25, v18, v19
	v_cvt_pk_bf16_f32 v26, v20, v21
	v_cvt_pk_bf16_f32 v27, v22, v23
	global_store_dwordx4 v6, v[24:27], s[48:49] sc1
	s_lshl_b32 s6, s2, 17
	s_add_u32 s9, s3, 0
	s_lshl_b32 s9, s9, 7
	s_add_u32 s6, s6, s9
	s_add_u32 s6, s6, 0x1c600000
	s_add_u32 s48, s28, s6
	s_addc_u32 s49, s29, 0
	ds_write2_b32 v10, v52, v53 offset1:1
	ds_write2_b32 v10, v54, v55 offset0:2 offset1:3
	ds_write2_b32 v11, v56, v57 offset1:1
	ds_write2_b32 v11, v58, v59 offset0:2 offset1:3
	s_waitcnt lgkmcnt(0)
	s_barrier
	ds_read2_b32 v[16:17], v14 offset1:65
	ds_read2_b32 v[18:19], v14 offset0:130 offset1:195
	ds_read2_b32 v[20:21], v15 offset1:65
	ds_read2_b32 v[22:23], v15 offset0:130 offset1:195
	s_waitcnt lgkmcnt(0)
	v_mul_f32_e32 v16, v16, v116
	v_mul_f32_e32 v17, v17, v117
	v_mul_f32_e32 v18, v18, v118
	v_mul_f32_e32 v19, v19, v119
	v_mul_f32_e32 v20, v20, v120
	v_mul_f32_e32 v21, v21, v121
	v_mul_f32_e32 v22, v22, v122
	v_mul_f32_e32 v23, v23, v123
	v_cvt_pk_bf16_f32 v28, v16, v17
	v_cvt_pk_bf16_f32 v29, v18, v19
	v_cvt_pk_bf16_f32 v30, v20, v21
	v_cvt_pk_bf16_f32 v31, v22, v23
	global_store_dwordx4 v6, v[28:31], s[48:49] sc1
	s_lshl_b32 s6, s2, 17
	s_add_u32 s9, s3, 4
	s_lshl_b32 s9, s9, 7
	s_add_u32 s6, s6, s9
	s_add_u32 s6, s6, 0x1c600000
	s_add_u32 s48, s28, s6
	s_addc_u32 s49, s29, 0
	ds_write2_b32 v8, v60, v61 offset1:1
	ds_write2_b32 v8, v62, v63 offset0:2 offset1:3
	ds_write2_b32 v9, v64, v65 offset1:1
	ds_write2_b32 v9, v66, v67 offset0:2 offset1:3
	s_waitcnt lgkmcnt(0)
	s_barrier
	ds_read2_b32 v[16:17], v12 offset1:65
	ds_read2_b32 v[18:19], v12 offset0:130 offset1:195
	ds_read2_b32 v[20:21], v13 offset1:65
	ds_read2_b32 v[22:23], v13 offset0:130 offset1:195
	s_waitcnt lgkmcnt(0)
	v_mul_f32_e32 v16, v16, v124
	v_mul_f32_e32 v17, v17, v125
	v_mul_f32_e32 v18, v18, v126
	v_mul_f32_e32 v19, v19, v127
	v_mul_f32_e32 v20, v20, v128
	v_mul_f32_e32 v21, v21, v129
	v_mul_f32_e32 v22, v22, v130
	v_mul_f32_e32 v23, v23, v131
	v_cvt_pk_bf16_f32 v24, v16, v17
	v_cvt_pk_bf16_f32 v25, v18, v19
	v_cvt_pk_bf16_f32 v26, v20, v21
	v_cvt_pk_bf16_f32 v27, v22, v23
	global_store_dwordx4 v6, v[24:27], s[48:49] sc1
	s_lshl_b32 s6, s2, 17
	s_add_u32 s9, s3, 8
	s_lshl_b32 s9, s9, 7
	s_add_u32 s6, s6, s9
	s_add_u32 s6, s6, 0x1c600000
	s_add_u32 s48, s28, s6
	s_addc_u32 s49, s29, 0
	ds_write2_b32 v10, v68, v69 offset1:1
	ds_write2_b32 v10, v70, v71 offset0:2 offset1:3
	ds_write2_b32 v11, v72, v73 offset1:1
	ds_write2_b32 v11, v74, v75 offset0:2 offset1:3
	s_waitcnt lgkmcnt(0)
	s_barrier
	ds_read2_b32 v[16:17], v14 offset1:65
	ds_read2_b32 v[18:19], v14 offset0:130 offset1:195
	ds_read2_b32 v[20:21], v15 offset1:65
	ds_read2_b32 v[22:23], v15 offset0:130 offset1:195
	s_waitcnt lgkmcnt(0)
	v_mul_f32_e32 v16, v16, v132
	v_mul_f32_e32 v17, v17, v133
	v_mul_f32_e32 v18, v18, v134
	v_mul_f32_e32 v19, v19, v135
	v_mul_f32_e32 v20, v20, v136
	v_mul_f32_e32 v21, v21, v137
	v_mul_f32_e32 v22, v22, v138
	v_mul_f32_e32 v23, v23, v139
	v_cvt_pk_bf16_f32 v28, v16, v17
	v_cvt_pk_bf16_f32 v29, v18, v19
	v_cvt_pk_bf16_f32 v30, v20, v21
	v_cvt_pk_bf16_f32 v31, v22, v23
	global_store_dwordx4 v6, v[28:31], s[48:49] sc1
	s_lshl_b32 s6, s2, 17
	s_add_u32 s9, s3, 12
	s_lshl_b32 s9, s9, 7
	s_add_u32 s6, s6, s9
	s_add_u32 s6, s6, 0x1c600000
	s_add_u32 s48, s28, s6
	s_addc_u32 s49, s29, 0
	ds_write2_b32 v8, v76, v77 offset1:1
	ds_write2_b32 v8, v78, v79 offset0:2 offset1:3
	ds_write2_b32 v9, v80, v81 offset1:1
	ds_write2_b32 v9, v82, v83 offset0:2 offset1:3
	s_waitcnt lgkmcnt(0)
	s_barrier
	ds_read2_b32 v[16:17], v12 offset1:65
	ds_read2_b32 v[18:19], v12 offset0:130 offset1:195
	ds_read2_b32 v[20:21], v13 offset1:65
	ds_read2_b32 v[22:23], v13 offset0:130 offset1:195
	s_waitcnt lgkmcnt(0)
	v_mul_f32_e32 v16, v16, v140
	v_mul_f32_e32 v17, v17, v141
	v_mul_f32_e32 v18, v18, v142
	v_mul_f32_e32 v19, v19, v143
	v_mul_f32_e32 v20, v20, v144
	v_mul_f32_e32 v21, v21, v145
	v_mul_f32_e32 v22, v22, v146
	v_mul_f32_e32 v23, v23, v147
	v_cvt_pk_bf16_f32 v24, v16, v17
	v_cvt_pk_bf16_f32 v25, v18, v19
	v_cvt_pk_bf16_f32 v26, v20, v21
	v_cvt_pk_bf16_f32 v27, v22, v23
	global_store_dwordx4 v6, v[24:27], s[48:49] sc1
	s_lshl_b32 s6, s0, 19
	s_add_u32 s9, s1, 0
	s_lshl_b32 s9, s9, 7
	s_add_u32 s6, s6, s9
	s_add_u32 s6, s6, 0x1ce00000
	s_add_u32 s48, s28, s6
	s_addc_u32 s49, s29, 0
	ds_write2_b32 v10, v84, v85 offset1:1
	ds_write2_b32 v10, v86, v87 offset0:2 offset1:3
	ds_write2_b32 v11, v88, v89 offset1:1
	ds_write2_b32 v11, v90, v91 offset0:2 offset1:3
	s_waitcnt lgkmcnt(0)
	s_barrier
	ds_read2_b32 v[16:17], v14 offset1:65
	ds_read2_b32 v[18:19], v14 offset0:130 offset1:195
	ds_read2_b32 v[20:21], v15 offset1:65
	ds_read2_b32 v[22:23], v15 offset0:130 offset1:195
	s_waitcnt lgkmcnt(0)
	v_cvt_pk_bf16_f32 v28, v16, v17
	v_cvt_pk_bf16_f32 v29, v18, v19
	v_cvt_pk_bf16_f32 v30, v20, v21
	v_cvt_pk_bf16_f32 v31, v22, v23
	global_store_dwordx4 v7, v[28:31], s[48:49] sc1
	s_lshl_b32 s6, s0, 19
	s_add_u32 s9, s1, 16
	s_lshl_b32 s9, s9, 7
	s_add_u32 s6, s6, s9
	s_add_u32 s6, s6, 0x1ce00000
	s_add_u32 s48, s28, s6
	s_addc_u32 s49, s29, 0
	ds_write2_b32 v8, v92, v93 offset1:1
	ds_write2_b32 v8, v94, v95 offset0:2 offset1:3
	ds_write2_b32 v9, v96, v97 offset1:1
	ds_write2_b32 v9, v98, v99 offset0:2 offset1:3
	s_waitcnt lgkmcnt(0)
	s_barrier
	ds_read2_b32 v[16:17], v12 offset1:65
	ds_read2_b32 v[18:19], v12 offset0:130 offset1:195
	ds_read2_b32 v[20:21], v13 offset1:65
	ds_read2_b32 v[22:23], v13 offset0:130 offset1:195
	s_waitcnt lgkmcnt(0)
	v_cvt_pk_bf16_f32 v24, v16, v17
	v_cvt_pk_bf16_f32 v25, v18, v19
	v_cvt_pk_bf16_f32 v26, v20, v21
	v_cvt_pk_bf16_f32 v27, v22, v23
	global_store_dwordx4 v7, v[24:27], s[48:49] sc1
	s_lshl_b32 s6, s0, 19
	s_add_u32 s9, s1, 32
	s_lshl_b32 s9, s9, 7
	s_add_u32 s6, s6, s9
	s_add_u32 s6, s6, 0x1ce00000
	s_add_u32 s48, s28, s6
	s_addc_u32 s49, s29, 0
	ds_write2_b32 v10, v100, v101 offset1:1
	ds_write2_b32 v10, v102, v103 offset0:2 offset1:3
	ds_write2_b32 v11, v104, v105 offset1:1
	ds_write2_b32 v11, v106, v107 offset0:2 offset1:3
	s_waitcnt lgkmcnt(0)
	s_barrier
	ds_read2_b32 v[16:17], v14 offset1:65
	ds_read2_b32 v[18:19], v14 offset0:130 offset1:195
	ds_read2_b32 v[20:21], v15 offset1:65
	ds_read2_b32 v[22:23], v15 offset0:130 offset1:195
	s_waitcnt lgkmcnt(0)
	v_cvt_pk_bf16_f32 v28, v16, v17
	v_cvt_pk_bf16_f32 v29, v18, v19
	v_cvt_pk_bf16_f32 v30, v20, v21
	v_cvt_pk_bf16_f32 v31, v22, v23
	global_store_dwordx4 v7, v[28:31], s[48:49] sc1
	s_lshl_b32 s6, s0, 19
	s_add_u32 s9, s1, 48
	s_lshl_b32 s9, s9, 7
	s_add_u32 s6, s6, s9
	s_add_u32 s6, s6, 0x1ce00000
	s_add_u32 s48, s28, s6
	s_addc_u32 s49, s29, 0
	ds_write2_b32 v8, v108, v109 offset1:1
	ds_write2_b32 v8, v110, v111 offset0:2 offset1:3
	ds_write2_b32 v9, v112, v113 offset1:1
	ds_write2_b32 v9, v114, v115 offset0:2 offset1:3
	s_waitcnt lgkmcnt(0)
	s_barrier
	ds_read2_b32 v[16:17], v12 offset1:65
	ds_read2_b32 v[18:19], v12 offset0:130 offset1:195
	ds_read2_b32 v[20:21], v13 offset1:65
	ds_read2_b32 v[22:23], v13 offset0:130 offset1:195
	s_waitcnt lgkmcnt(0)
	v_cvt_pk_bf16_f32 v24, v16, v17
	v_cvt_pk_bf16_f32 v25, v18, v19
	v_cvt_pk_bf16_f32 v26, v20, v21
	v_cvt_pk_bf16_f32 v27, v22, v23
	global_store_dwordx4 v7, v[24:27], s[48:49] sc1
	s_branch .LBB0_380
